# no L2 writeback at the pair barrier that only guards a write-after-read; idle-slot weight conversion stores written through
# speedup vs baseline: 1.0100x; 1.0090x over previous
; __device__ __forceinline__ unsigned xb_add(unsigned* p, unsigned v) { return __hip_atomic_fetch_add(p, v, __ATOMIC_RELAXED, __HIP_MEMORY_SCOPE_AGENT); }
; __device__ __forceinline__ void xcd_barrier(const XcdBarrier& b, bool tid0) {
;     ...
;         if (old + 1u == (gen + 1u) * nloc) {
;             __builtin_amdgcn_fence(__ATOMIC_RELEASE, "agent");
;             asm volatile("s_waitcnt vmcnt(0)" ::: "memory");
;             const unsigned og = xb_add(&bar[XB_TOP], 1u);
.LBB0_203:
	s_andn2_saveexec_b64 s[0:1], s[8:9]
	s_cbranch_execz .LBB0_223
	s_mov_b64 s[0:1], exec
	s_waitcnt lgkmcnt(0)
	s_waitcnt vmcnt(0)
	v_mbcnt_lo_u32_b32 v1, s0, 0
	v_mbcnt_hi_u32_b32 v1, s1, v1
	v_cmp_eq_u32_e32 vcc, 0, v1
	s_and_saveexec_b64 s[8:9], vcc
	s_cbranch_execz .LBB0_206
	s_bcnt1_i32_b64 s0, s[0:1]
	v_mov_b32_e32 v2, s0
	v_mov_b32_e32 v3, 0x26123000
	global_atomic_add v2, v3, v2, s[4:5] offset:1024 sc0

; #define LAS __attribute__((address_space(3)))
; __device__ __forceinline__ void conv_item(const float* __restrict__ W, int N, bf16_t* __restrict__ WT, int ldk, int mode, int row_off, int n_lo, int nblk, ...
;     const int kb = item / nblk, nb = item % nblk, k0 = 64 * kb, n0 = n_lo + 32 * nb;
;     const float s = sc * (sn ? sn[n0 + (lane & 31)] : 1.f);
;     const float* wp = W + (size_t)(k0 + (lane >> 5)) * N + n0 + (lane & 31);
;     float v[32];
; #pragma unroll
;     for (int i = 0; i < 32; ++i) v[i] = __builtin_nontemporal_load(wp + (size_t)(2 * i) * N);
; #pragma unroll
;     for (int i = 0; i < 32; ++i) scr[(2 * i + (lane >> 5)) * 33 + (lane & 31)] = v[i] * s;
.LBB0_704:
	s_ashr_i32 s14, s24, 31
	s_lshr_b32 s14, s14, 26
	s_add_i32 s14, s24, s14
	s_ashr_i32 s28, s14, 6
	s_andn2_b32 s14, s14, 63
	v_or_b32_e32 v6, s14, v1
	s_lshl_b32 s15, s28, 11
	v_ashrrev_i32_e32 v7, 31, v6
	s_sub_i32 s30, s25, s15
	v_lshlrev_b64 v[6:7], 13, v[6:7]
	v_lshl_add_u64 v[6:7], s[12:13], 0, v[6:7]
	s_ashr_i32 s31, s30, 31
	v_lshl_add_u64 v[6:7], s[30:31], 2, v[6:7]
	v_lshl_add_u64 v[6:7], v[6:7], 0, v[176:177]
	v_add_co_u32_e32 v18, vcc, s94, v6
	global_load_dword v11, v[6:7], off nt
	s_nop 0
	v_addc_co_u32_e32 v19, vcc, 0, v7, vcc
	global_load_dword v17, v[18:19], off nt
	v_add_co_u32_e32 v18, vcc, s36, v6
	s_mul_i32 s28, s28, 0xff500000
	s_nop 0
	v_addc_co_u32_e32 v19, vcc, 0, v7, vcc
	global_load_dword v20, v[18:19], off nt
	v_add_co_u32_e32 v18, vcc, s97, v6
	s_ashr_i32 s15, s14, 31
	s_nop 0
	v_addc_co_u32_e32 v19, vcc, 0, v7, vcc
	global_load_dword v21, v[18:19], off nt
	v_add_co_u32_e32 v18, vcc, s96, v6
	s_add_i32 s24, s24, s88
	s_nop 0
	v_addc_co_u32_e32 v19, vcc, 0, v7, vcc
	global_load_dword v22, v[18:19], off nt
	v_add_co_u32_e32 v18, vcc, s69, v6
	s_add_i32 s25, s25, s27
	s_nop 0
	v_addc_co_u32_e32 v19, vcc, 0, v7, vcc
	global_load_dword v23, v[18:19], off nt
	v_add_co_u32_e32 v18, vcc, s37, v6
	s_cmpk_lt_i32 s24, 0x1600
	s_nop 0
	v_addc_co_u32_e32 v19, vcc, 0, v7, vcc
	global_load_dword v24, v[18:19], off nt
	v_add_co_u32_e32 v18, vcc, s39, v6
	s_nop 1
	v_addc_co_u32_e32 v19, vcc, 0, v7, vcc
	global_load_dword v25, v[18:19], off nt
	v_add_co_u32_e32 v18, vcc, s38, v6
	s_nop 1
	v_addc_co_u32_e32 v19, vcc, 0, v7, vcc
	global_load_dword v26, v[18:19], off nt
	v_add_co_u32_e32 v18, vcc, s52, v6
	s_nop 1
	v_addc_co_u32_e32 v19, vcc, 0, v7, vcc
	global_load_dword v27, v[18:19], off nt
	v_add_co_u32_e32 v18, vcc, s53, v6
	s_nop 1
	v_addc_co_u32_e32 v19, vcc, 0, v7, vcc
	global_load_dword v28, v[18:19], off nt
	v_add_co_u32_e32 v18, vcc, s29, v6
	s_nop 1
	v_addc_co_u32_e32 v19, vcc, 0, v7, vcc
	global_load_dword v29, v[18:19], off nt
	v_add_co_u32_e32 v18, vcc, s35, v6
	s_nop 1
	v_addc_co_u32_e32 v19, vcc, 0, v7, vcc
	global_load_dword v30, v[18:19], off nt
	v_add_co_u32_e32 v18, vcc, s58, v6
	s_nop 1
	v_addc_co_u32_e32 v19, vcc, 0, v7, vcc
	global_load_dword v31, v[18:19], off nt
	v_add_co_u32_e32 v18, vcc, s59, v6
	s_nop 1
	v_addc_co_u32_e32 v19, vcc, 0, v7, vcc
	global_load_dword v32, v[18:19], off nt
	v_add_co_u32_e32 v18, vcc, s60, v6
	s_nop 1
	v_addc_co_u32_e32 v19, vcc, 0, v7, vcc
	global_load_dword v33, v[18:19], off nt
	v_add_co_u32_e32 v18, vcc, s34, v6
	s_nop 1
	v_addc_co_u32_e32 v19, vcc, 0, v7, vcc
	global_load_dword v34, v[18:19], off nt
	v_add_co_u32_e32 v18, vcc, s61, v6
	s_nop 1
	v_addc_co_u32_e32 v19, vcc, 0, v7, vcc
	global_load_dword v35, v[18:19], off nt
	v_add_co_u32_e32 v18, vcc, s62, v6
	s_nop 1
	v_addc_co_u32_e32 v19, vcc, 0, v7, vcc
	global_load_dword v36, v[18:19], off nt
	v_add_co_u32_e32 v18, vcc, s63, v6
	s_nop 1
	v_addc_co_u32_e32 v19, vcc, 0, v7, vcc
	global_load_dword v37, v[18:19], off nt
	v_add_co_u32_e32 v18, vcc, s41, v6
	s_nop 1
	v_addc_co_u32_e32 v19, vcc, 0, v7, vcc
	global_load_dword v38, v[18:19], off nt
	v_add_co_u32_e32 v18, vcc, s42, v6
	s_nop 1
	v_addc_co_u32_e32 v19, vcc, 0, v7, vcc
	global_load_dword v39, v[18:19], off nt
	v_add_co_u32_e32 v18, vcc, s43, v6
	s_nop 1
	v_addc_co_u32_e32 v19, vcc, 0, v7, vcc
	global_load_dword v40, v[18:19], off nt
	v_add_co_u32_e32 v18, vcc, s44, v6
	s_nop 1
	v_addc_co_u32_e32 v19, vcc, 0, v7, vcc
	global_load_dword v41, v[18:19], off nt
	v_add_co_u32_e32 v18, vcc, s49, v6
	s_nop 1
	v_addc_co_u32_e32 v19, vcc, 0, v7, vcc
	global_load_dword v42, v[18:19], off nt
	v_add_co_u32_e32 v18, vcc, s45, v6
	s_nop 1
	v_addc_co_u32_e32 v19, vcc, 0, v7, vcc
	global_load_dword v43, v[18:19], off nt
	v_add_co_u32_e32 v18, vcc, s46, v6
	s_nop 1
	v_addc_co_u32_e32 v19, vcc, 0, v7, vcc
	global_load_dword v44, v[18:19], off nt
	v_add_co_u32_e32 v18, vcc, s47, v6
	s_nop 1
	v_addc_co_u32_e32 v19, vcc, 0, v7, vcc
	global_load_dword v45, v[18:19], off nt
	v_add_co_u32_e32 v18, vcc, s48, v6
	s_nop 1
	v_addc_co_u32_e32 v19, vcc, 0, v7, vcc
	global_load_dword v46, v[18:19], off nt
	v_add_co_u32_e32 v18, vcc, s50, v6
	s_nop 1
	v_addc_co_u32_e32 v19, vcc, 0, v7, vcc
	global_load_dword v47, v[18:19], off nt
	v_add_co_u32_e32 v18, vcc, s64, v6
	s_nop 1
	v_addc_co_u32_e32 v19, vcc, 0, v7, vcc
	v_add_co_u32_e32 v6, vcc, s65, v6
	global_load_dword v18, v[18:19], off nt
	s_nop 0
	v_addc_co_u32_e32 v7, vcc, 0, v7, vcc
	global_load_dword v6, v[6:7], off nt
	v_add_u32_e32 v7, 0x400, v10
	s_waitcnt vmcnt(0)
; #define LAS __attribute__((address_space(3)))
; __device__ __forceinline__ unsigned cvt_pk_bf16(float lo, float hi) { unsigned r; asm("v_cvt_pk_bf16_f32 %0, %1, %2" : "=v"(r) : "v"(lo), "v"(hi)); return r; }
; __device__ __forceinline__ unsigned cvt_pk_f16(float lo, float hi) { if (X_BF16) return cvt_pk_bf16(lo, hi); const h16x2 v = {(_Float16)lo, (_Float16)hi}; return __builtin_bit_cast(unsigned, v); }
; __device__ __forceinline__ void conv_item(const float* __restrict__ W, int N, bf16_t* __restrict__ WT, int ldk, int mode, int row_off, int n_lo, int nblk, ...
;     ...
;     for (int i = 0; i < 32; ++i) scr[(2 * i + (lane >> 5)) * 33 + (lane & 31)] = v[i] * s;
;     asm volatile("s_waitcnt lgkmcnt(0)" ::: "memory");
;     const int c = lane & 7;
;     f32x4 g0 = {1.f, 1.f, 1.f, 1.f}, g1 = g0;
;     if (gk) { g0 = *(const f32x4*)(gk + k0 + 8 * c); g1 = *(const f32x4*)(gk + k0 + 8 * c + 4); }
;     const int nn0 = n0 - n_lo;
;     const int drow0 = (mode == 0) ? row_off + nn0 : 256 * (nn0 >> 7) + 128 * (mode - 1) + (nn0 & 127);
; #pragma unroll
;     for (int j = 0; j < 4; ++j) { const int n = (lane >> 3) + 8 * j; const LAS float* sp = scr + (8 * c) * 33 + n;
;         const float e0 = sp[0 * 33] * g0[0], e1 = sp[1 * 33] * g0[1], e2 = sp[2 * 33] * g0[2], e3 = sp[3 * 33] * g0[3], e4 = sp[4 * 33] * g1[0], e5 = sp[5 * 33] * g1[1], e6 = sp[6 * 33] * g1[2], e7 = sp[7 * 33] * g1[3];
;         u32x4 o;
;         if (f16) { o.x = pg8::cvt_pk_f16(e0, e1); o.y = pg8::cvt_pk_f16(e2, e3); o.z = pg8::cvt_pk_f16(e4, e5); o.w = pg8::cvt_pk_f16(e6, e7); }
;         else { o.x = cvt_pk_bf16(e0, e1); o.y = cvt_pk_bf16(e2, e3); o.z = cvt_pk_bf16(e4, e5); o.w = cvt_pk_bf16(e6, e7); }
;         *(u32x4*)(WT + (size_t)(drow0 + n) * ldk + k0 + 8 * c) = o; }
;     asm volatile("s_waitcnt lgkmcnt(0)" ::: "memory");
	ds_write2_b32 v10, v11, v17 offset1:66
	ds_write2_b32 v10, v20, v21 offset0:132 offset1:198
	ds_write2_b32 v7, v22, v23 offset0:8 offset1:74
	ds_write2_b32 v7, v24, v25 offset0:140 offset1:206
	v_add_u32_e32 v7, 0x800, v10
	ds_write2_b32 v7, v26, v27 offset0:16 offset1:82
	ds_write2_b32 v7, v28, v29 offset0:148 offset1:214
	v_add_u32_e32 v7, 0xc00, v10
	ds_write2_b32 v7, v30, v31 offset0:24 offset1:90
	ds_write2_b32 v7, v32, v33 offset0:156 offset1:222
	v_add_u32_e32 v7, 0x1000, v10
	ds_write2_b32 v7, v34, v35 offset0:32 offset1:98
	ds_write2_b32 v7, v36, v37 offset0:164 offset1:230
	v_add_u32_e32 v7, 0x1400, v10
	ds_write2_b32 v7, v38, v39 offset0:40 offset1:106
	ds_write2_b32 v7, v40, v41 offset0:172 offset1:238
	v_add_u32_e32 v7, 0x1800, v10
	ds_write2_b32 v7, v42, v43 offset0:48 offset1:114
	ds_write2_b32 v7, v44, v45 offset0:180 offset1:246
	v_add_u32_e32 v7, 0x1c00, v10
	ds_write2_b32 v7, v46, v47 offset0:56 offset1:122
	ds_write2_b32 v7, v18, v6 offset0:188 offset1:254
	s_waitcnt lgkmcnt(0)
	ds_read2_b32 v[22:23], v3 offset0:33 offset1:41
	ds_read2_b32 v[24:25], v3 offset1:8
	ds_read2_b32 v[26:27], v3 offset0:66 offset1:74
	ds_read2_b32 v[28:29], v3 offset0:99 offset1:107
	ds_read2_b32 v[30:31], v3 offset0:132 offset1:140
	ds_read2_b32 v[32:33], v3 offset0:165 offset1:173
	ds_read2_b32 v[34:35], v3 offset0:198 offset1:206
	ds_read2_b32 v[36:37], v3 offset0:231 offset1:239
	v_add_u32_e32 v38, s28, v9
	v_lshl_add_u64 v[6:7], s[14:15], 1, v[4:5]
	v_ashrrev_i32_e32 v39, 31, v38
	s_waitcnt lgkmcnt(6)
	v_cvt_pk_bf16_f32 v18, v24, v22
	v_lshl_add_u64 v[40:41], v[38:39], 1, v[6:7]
	v_add_u32_e32 v22, 0xb000, v38
	s_waitcnt lgkmcnt(4)
	v_cvt_pk_bf16_f32 v19, v26, v28
	s_waitcnt lgkmcnt(2)
	v_cvt_pk_bf16_f32 v20, v30, v32
	s_waitcnt lgkmcnt(0)
	v_cvt_pk_bf16_f32 v21, v34, v36
	global_store_dwordx4 v[40:41], v[18:21], off sc0 sc1
	v_add_u32_e32 v40, 0x16000, v38
	v_ashrrev_i32_e32 v41, 31, v40
	v_cvt_pk_bf16_f32 v18, v25, v23
	v_ashrrev_i32_e32 v23, 31, v22
	v_lshl_add_u64 v[22:23], v[22:23], 1, v[6:7]
	v_cvt_pk_bf16_f32 v19, v27, v29
	v_cvt_pk_bf16_f32 v20, v31, v33
	v_cvt_pk_bf16_f32 v21, v35, v37
	global_store_dwordx4 v[22:23], v[18:21], off sc0 sc1
	ds_read2_b32 v[22:23], v3 offset0:16 offset1:24
	ds_read2_b32 v[24:25], v3 offset0:49 offset1:57
	ds_read2_b32 v[26:27], v3 offset0:82 offset1:90
	ds_read2_b32 v[28:29], v3 offset0:115 offset1:123
	ds_read2_b32 v[30:31], v3 offset0:148 offset1:156
	ds_read2_b32 v[32:33], v3 offset0:181 offset1:189
	ds_read2_b32 v[34:35], v3 offset0:214 offset1:222
	ds_read2_b32 v[36:37], v3 offset0:247 offset1:255
	s_waitcnt lgkmcnt(6)
	v_cvt_pk_bf16_f32 v18, v22, v24
	v_lshl_add_u64 v[40:41], v[40:41], 1, v[6:7]
	v_add_u32_e32 v22, 0x21000, v38
	s_waitcnt lgkmcnt(4)
	v_cvt_pk_bf16_f32 v19, v26, v28
	s_waitcnt lgkmcnt(2)
	v_cvt_pk_bf16_f32 v20, v30, v32
	s_waitcnt lgkmcnt(0)
	v_cvt_pk_bf16_f32 v21, v34, v36
	global_store_dwordx4 v[40:41], v[18:21], off sc0 sc1
	s_mul_i32 s14, s88, 0x2c000
	v_add_u32_e32 v9, s14, v9
	v_cvt_pk_bf16_f32 v18, v23, v25
	v_ashrrev_i32_e32 v23, 31, v22
	v_lshl_add_u64 v[6:7], v[22:23], 1, v[6:7]
	v_cvt_pk_bf16_f32 v19, v27, v29
	v_cvt_pk_bf16_f32 v20, v31, v33
	v_cvt_pk_bf16_f32 v21, v35, v37
	global_store_dwordx4 v[6:7], v[18:21], off sc0 sc1
	s_waitcnt lgkmcnt(0)
	s_cbranch_scc1 .LBB0_704

; #define LAS __attribute__((address_space(3)))
; __device__ __forceinline__ void conv_item(const float* __restrict__ W, int N, bf16_t* __restrict__ WT, int ldk, int mode, int row_off, int n_lo, int nblk, ...
;     const int kb = item / nblk, nb = item % nblk, k0 = 64 * kb, n0 = n_lo + 32 * nb;
;     const float s = sc * (sn ? sn[n0 + (lane & 31)] : 1.f);
;     const float* wp = W + (size_t)(k0 + (lane >> 5)) * N + n0 + (lane & 31);
;     float v[32];
; #pragma unroll
;     for (int i = 0; i < 32; ++i) v[i] = __builtin_nontemporal_load(wp + (size_t)(2 * i) * N);
; #pragma unroll
;     for (int i = 0; i < 32; ++i) scr[(2 * i + (lane >> 5)) * 33 + (lane & 31)] = v[i] * s;
.LBB0_707:
	s_ashr_i32 s14, s27, 31
	s_lshr_b32 s14, s14, 26
	s_add_i32 s14, s27, s14
	s_and_b32 s24, s14, 0xffffffc0
	s_lshl_b32 s14, s14, 5
	v_or_b32_e32 v10, s24, v1
	s_and_b32 s14, s14, 0xfffff800
	v_ashrrev_i32_e32 v11, 31, v10
	s_sub_i32 s14, s28, s14
	v_lshlrev_b64 v[10:11], 13, v[10:11]
	v_lshl_add_u64 v[10:11], s[12:13], 0, v[10:11]
	s_ashr_i32 s15, s14, 31
	v_lshl_add_u64 v[10:11], s[14:15], 2, v[10:11]
	v_lshl_add_u64 v[10:11], v[10:11], 0, v[176:177]
	v_add_co_u32_e32 v18, vcc, s94, v10
	global_load_dword v17, v[10:11], off nt
	s_nop 0
	v_addc_co_u32_e32 v19, vcc, 0, v11, vcc
	global_load_dword v20, v[18:19], off nt
	v_add_co_u32_e32 v18, vcc, s36, v10
	s_ashr_i32 s25, s24, 31
	s_nop 0
	v_addc_co_u32_e32 v19, vcc, 0, v11, vcc
	global_load_dword v21, v[18:19], off nt
	v_add_co_u32_e32 v18, vcc, s97, v10
	s_add_i32 s27, s27, s88
	s_nop 0
	v_addc_co_u32_e32 v19, vcc, 0, v11, vcc
	global_load_dword v22, v[18:19], off nt
	v_add_co_u32_e32 v18, vcc, s96, v10
	s_add_i32 s28, s28, s29
	s_nop 0
	v_addc_co_u32_e32 v19, vcc, 0, v11, vcc
	global_load_dword v23, v[18:19], off nt
	v_add_co_u32_e32 v18, vcc, s69, v10
	s_cmpk_lt_i32 s27, 0x800
	s_nop 0
	v_addc_co_u32_e32 v19, vcc, 0, v11, vcc
	global_load_dword v24, v[18:19], off nt
	v_add_co_u32_e32 v18, vcc, s37, v10
	s_nop 1
	v_addc_co_u32_e32 v19, vcc, 0, v11, vcc
	global_load_dword v25, v[18:19], off nt
	v_add_co_u32_e32 v18, vcc, s39, v10
	s_nop 1
	v_addc_co_u32_e32 v19, vcc, 0, v11, vcc
	global_load_dword v26, v[18:19], off nt
	v_add_co_u32_e32 v18, vcc, s38, v10
	s_nop 1
	v_addc_co_u32_e32 v19, vcc, 0, v11, vcc
	global_load_dword v27, v[18:19], off nt
	v_add_co_u32_e32 v18, vcc, s52, v10
	s_nop 1
	v_addc_co_u32_e32 v19, vcc, 0, v11, vcc
	global_load_dword v28, v[18:19], off nt
	v_add_co_u32_e32 v18, vcc, s53, v10
	s_nop 1
	v_addc_co_u32_e32 v19, vcc, 0, v11, vcc
	global_load_dword v29, v[18:19], off nt
	v_add_co_u32_e32 v18, vcc, s30, v10
	s_nop 1
	v_addc_co_u32_e32 v19, vcc, 0, v11, vcc
	global_load_dword v30, v[18:19], off nt
	v_add_co_u32_e32 v18, vcc, s35, v10
	s_nop 1
	v_addc_co_u32_e32 v19, vcc, 0, v11, vcc
	global_load_dword v31, v[18:19], off nt
	v_add_co_u32_e32 v18, vcc, s58, v10
	s_nop 1
	v_addc_co_u32_e32 v19, vcc, 0, v11, vcc
	global_load_dword v32, v[18:19], off nt
	v_add_co_u32_e32 v18, vcc, s59, v10
	s_nop 1
	v_addc_co_u32_e32 v19, vcc, 0, v11, vcc
	global_load_dword v33, v[18:19], off nt
	v_add_co_u32_e32 v18, vcc, s60, v10
	s_nop 1
	v_addc_co_u32_e32 v19, vcc, 0, v11, vcc
	global_load_dword v34, v[18:19], off nt
	v_add_co_u32_e32 v18, vcc, s34, v10
	s_nop 1
	v_addc_co_u32_e32 v19, vcc, 0, v11, vcc
	global_load_dword v35, v[18:19], off nt
	v_add_co_u32_e32 v18, vcc, s61, v10
	s_nop 1
	v_addc_co_u32_e32 v19, vcc, 0, v11, vcc
	global_load_dword v36, v[18:19], off nt
	v_add_co_u32_e32 v18, vcc, s62, v10
	s_nop 1
	v_addc_co_u32_e32 v19, vcc, 0, v11, vcc
	global_load_dword v37, v[18:19], off nt
	v_add_co_u32_e32 v18, vcc, s63, v10
	s_nop 1
	v_addc_co_u32_e32 v19, vcc, 0, v11, vcc
	global_load_dword v38, v[18:19], off nt
	v_add_co_u32_e32 v18, vcc, s31, v10
	s_nop 1
	v_addc_co_u32_e32 v19, vcc, 0, v11, vcc
	global_load_dword v39, v[18:19], off nt
	v_add_co_u32_e32 v18, vcc, s41, v10
	s_nop 1
	v_addc_co_u32_e32 v19, vcc, 0, v11, vcc
	global_load_dword v40, v[18:19], off nt
	v_add_co_u32_e32 v18, vcc, s42, v10
	s_nop 1
	v_addc_co_u32_e32 v19, vcc, 0, v11, vcc
	global_load_dword v41, v[18:19], off nt
	v_add_co_u32_e32 v18, vcc, s43, v10
	s_nop 1
	v_addc_co_u32_e32 v19, vcc, 0, v11, vcc
	global_load_dword v42, v[18:19], off nt
	v_add_co_u32_e32 v18, vcc, s49, v10
	s_nop 1
	v_addc_co_u32_e32 v19, vcc, 0, v11, vcc
	global_load_dword v43, v[18:19], off nt
	v_add_co_u32_e32 v18, vcc, s44, v10
	s_nop 1
	v_addc_co_u32_e32 v19, vcc, 0, v11, vcc
	global_load_dword v44, v[18:19], off nt
	v_add_co_u32_e32 v18, vcc, s45, v10
	s_nop 1
	v_addc_co_u32_e32 v19, vcc, 0, v11, vcc
	global_load_dword v45, v[18:19], off nt
	v_add_co_u32_e32 v18, vcc, s46, v10
	s_nop 1
	v_addc_co_u32_e32 v19, vcc, 0, v11, vcc
	global_load_dword v46, v[18:19], off nt
	v_add_co_u32_e32 v18, vcc, s47, v10
	s_nop 1
	v_addc_co_u32_e32 v19, vcc, 0, v11, vcc
	global_load_dword v47, v[18:19], off nt
	v_add_co_u32_e32 v18, vcc, s48, v10
	s_nop 1
	v_addc_co_u32_e32 v19, vcc, 0, v11, vcc
	global_load_dword v48, v[18:19], off nt
	v_add_co_u32_e32 v18, vcc, s64, v10
	s_nop 1
	v_addc_co_u32_e32 v19, vcc, 0, v11, vcc
	v_add_co_u32_e32 v10, vcc, s65, v10
	global_load_dword v18, v[18:19], off nt
	s_nop 0
	v_addc_co_u32_e32 v11, vcc, 0, v11, vcc
	global_load_dword v10, v[10:11], off nt
	v_add_u32_e32 v11, 0x400, v5
	s_waitcnt vmcnt(0)
; #define LAS __attribute__((address_space(3)))
; __device__ __forceinline__ unsigned cvt_pk_bf16(float lo, float hi) { unsigned r; asm("v_cvt_pk_bf16_f32 %0, %1, %2" : "=v"(r) : "v"(lo), "v"(hi)); return r; }
; __device__ __forceinline__ unsigned cvt_pk_f16(float lo, float hi) { if (X_BF16) return cvt_pk_bf16(lo, hi); const h16x2 v = {(_Float16)lo, (_Float16)hi}; return __builtin_bit_cast(unsigned, v); }
; __device__ __forceinline__ void conv_item(const float* __restrict__ W, int N, bf16_t* __restrict__ WT, int ldk, int mode, int row_off, int n_lo, int nblk, ...
;     ...
;     for (int i = 0; i < 32; ++i) scr[(2 * i + (lane >> 5)) * 33 + (lane & 31)] = v[i] * s;
;     asm volatile("s_waitcnt lgkmcnt(0)" ::: "memory");
;     const int c = lane & 7;
;     f32x4 g0 = {1.f, 1.f, 1.f, 1.f}, g1 = g0;
;     if (gk) { g0 = *(const f32x4*)(gk + k0 + 8 * c); g1 = *(const f32x4*)(gk + k0 + 8 * c + 4); }
;     const int nn0 = n0 - n_lo;
;     const int drow0 = (mode == 0) ? row_off + nn0 : 256 * (nn0 >> 7) + 128 * (mode - 1) + (nn0 & 127);
; #pragma unroll
;     for (int j = 0; j < 4; ++j) { const int n = (lane >> 3) + 8 * j; const LAS float* sp = scr + (8 * c) * 33 + n;
;         const float e0 = sp[0 * 33] * g0[0], e1 = sp[1 * 33] * g0[1], e2 = sp[2 * 33] * g0[2], e3 = sp[3 * 33] * g0[3], e4 = sp[4 * 33] * g1[0], e5 = sp[5 * 33] * g1[1], e6 = sp[6 * 33] * g1[2], e7 = sp[7 * 33] * g1[3];
;         u32x4 o;
;         if (f16) { o.x = pg8::cvt_pk_f16(e0, e1); o.y = pg8::cvt_pk_f16(e2, e3); o.z = pg8::cvt_pk_f16(e4, e5); o.w = pg8::cvt_pk_f16(e6, e7); }
;         else { o.x = cvt_pk_bf16(e0, e1); o.y = cvt_pk_bf16(e2, e3); o.z = cvt_pk_bf16(e4, e5); o.w = cvt_pk_bf16(e6, e7); }
;         *(u32x4*)(WT + (size_t)(drow0 + n) * ldk + k0 + 8 * c) = o; }
;     asm volatile("s_waitcnt lgkmcnt(0)" ::: "memory");
	ds_write2_b32 v5, v17, v20 offset1:66
	ds_write2_b32 v5, v21, v22 offset0:132 offset1:198
	ds_write2_b32 v11, v23, v24 offset0:8 offset1:74
	ds_write2_b32 v11, v25, v26 offset0:140 offset1:206
	v_add_u32_e32 v11, 0x800, v5
	ds_write2_b32 v11, v27, v28 offset0:16 offset1:82
	ds_write2_b32 v11, v29, v30 offset0:148 offset1:214
	v_add_u32_e32 v11, 0xc00, v5
	ds_write2_b32 v11, v31, v32 offset0:24 offset1:90
	ds_write2_b32 v11, v33, v34 offset0:156 offset1:222
	v_add_u32_e32 v11, 0x1000, v5
	ds_write2_b32 v11, v35, v36 offset0:32 offset1:98
	ds_write2_b32 v11, v37, v38 offset0:164 offset1:230
	v_add_u32_e32 v11, 0x1400, v5
	ds_write2_b32 v11, v39, v40 offset0:40 offset1:106
	ds_write2_b32 v11, v41, v42 offset0:172 offset1:238
	v_add_u32_e32 v11, 0x1800, v5
	ds_write2_b32 v11, v43, v44 offset0:48 offset1:114
	ds_write2_b32 v11, v45, v46 offset0:180 offset1:246
	v_add_u32_e32 v11, 0x1c00, v5
	ds_write2_b32 v11, v47, v48 offset0:56 offset1:122
	ds_write2_b32 v11, v18, v10 offset0:188 offset1:254
	s_waitcnt lgkmcnt(0)
	v_lshl_add_u64 v[10:11], s[24:25], 2, v[6:7]
	global_load_dwordx4 v[18:21], v[10:11], off offset:16
	global_load_dwordx4 v[22:25], v[10:11], off
	ds_read2_b32 v[34:35], v3 offset0:66 offset1:74
	ds_read2_b32 v[36:37], v3 offset0:99 offset1:107
	ds_read2_b32 v[30:31], v3 offset1:8
	ds_read2_b32 v[32:33], v3 offset0:33 offset1:41
	ds_read2_b32 v[38:39], v3 offset0:132 offset1:140
	ds_read2_b32 v[40:41], v3 offset0:165 offset1:173
	ds_read2_b32 v[42:43], v3 offset0:198 offset1:206
	ds_read2_b32 v[44:45], v3 offset0:231 offset1:239
	v_add_u32_e32 v46, s14, v12
	v_ashrrev_i32_e32 v47, 31, v46
	v_lshl_add_u64 v[10:11], s[24:25], 1, v[8:9]
	v_lshlrev_b64 v[48:49], 12, v[46:47]
	v_lshl_add_u64 v[48:49], v[10:11], 0, v[48:49]
	s_waitcnt vmcnt(1) lgkmcnt(3)
	v_mul_f32_e32 v29, v18, v38
	s_waitcnt vmcnt(0)
	v_mul_f32_e32 v27, v24, v34
	v_mul_f32_e32 v28, v25, v36
	v_mul_f32_e32 v17, v22, v30
	v_mul_f32_e32 v26, v23, v32
	s_waitcnt lgkmcnt(2)
	v_mul_f32_e32 v30, v19, v40
	v_cvt_pk_bf16_f32 v27, v27, v28
	v_cvt_pk_bf16_f32 v28, v29, v30
	s_waitcnt lgkmcnt(1)
	v_mul_f32_e32 v32, v20, v42
	s_waitcnt lgkmcnt(0)
	v_mul_f32_e32 v34, v21, v44
	v_cvt_pk_bf16_f32 v26, v17, v26
	v_cvt_pk_bf16_f32 v29, v32, v34
	global_store_dwordx4 v[48:49], v[26:29], off sc0 sc1
	v_mul_f32_e32 v30, v19, v41
	v_mul_f32_e32 v17, v22, v31
	v_mul_f32_e32 v27, v24, v35
	v_mul_f32_e32 v28, v25, v37
	v_mul_f32_e32 v29, v18, v39
	v_mul_f32_e32 v31, v20, v43
	v_cvt_pk_bf16_f32 v27, v27, v28
	v_cvt_pk_bf16_f32 v28, v29, v30
	v_add_u32_e32 v30, 8, v46
	v_mul_f32_e32 v32, v21, v45
	v_cvt_pk_bf16_f32 v29, v31, v32
	v_ashrrev_i32_e32 v31, 31, v30
	v_lshlrev_b64 v[30:31], 12, v[30:31]
	v_mul_f32_e32 v26, v23, v33
	v_lshl_add_u64 v[30:31], v[10:11], 0, v[30:31]
	v_cvt_pk_bf16_f32 v26, v17, v26
	global_store_dwordx4 v[30:31], v[26:29], off sc0 sc1
	ds_read2_b32 v[30:31], v3 offset0:16 offset1:24
	ds_read2_b32 v[32:33], v3 offset0:49 offset1:57
	ds_read2_b32 v[34:35], v3 offset0:82 offset1:90
	ds_read2_b32 v[36:37], v3 offset0:115 offset1:123
	ds_read2_b32 v[38:39], v3 offset0:148 offset1:156
	ds_read2_b32 v[40:41], v3 offset0:181 offset1:189
	ds_read2_b32 v[42:43], v3 offset0:214 offset1:222
	ds_read2_b32 v[44:45], v3 offset0:247 offset1:255
	v_add_u32_e32 v48, 16, v46
	s_waitcnt lgkmcnt(7)
	v_mul_f32_e32 v17, v22, v30
	s_waitcnt lgkmcnt(6)
	v_mul_f32_e32 v26, v23, v32
	v_ashrrev_i32_e32 v49, 31, v48
	v_cvt_pk_bf16_f32 v26, v17, v26
	v_lshlrev_b64 v[48:49], 12, v[48:49]
	v_mul_f32_e32 v17, v22, v31
	v_mul_f32_e32 v22, v23, v33
	s_waitcnt lgkmcnt(5)
	v_mul_f32_e32 v27, v24, v34
	s_waitcnt lgkmcnt(4)
	v_mul_f32_e32 v28, v25, v36
	s_waitcnt lgkmcnt(3)
	v_mul_f32_e32 v29, v18, v38
	v_lshl_add_u64 v[48:49], v[10:11], 0, v[48:49]
	v_mul_f32_e32 v23, v24, v35
	v_mul_f32_e32 v24, v25, v37
	v_mul_f32_e32 v25, v18, v39
	v_cvt_pk_bf16_f32 v18, v17, v22
	v_add_u32_e32 v22, 24, v46
	s_waitcnt lgkmcnt(2)
	v_mul_f32_e32 v30, v19, v40
	s_waitcnt lgkmcnt(1)
	v_mul_f32_e32 v32, v20, v42
	s_waitcnt lgkmcnt(0)
	v_mul_f32_e32 v34, v21, v44
	v_cvt_pk_bf16_f32 v27, v27, v28
	v_cvt_pk_bf16_f32 v28, v29, v30
	v_cvt_pk_bf16_f32 v29, v32, v34
	global_store_dwordx4 v[48:49], v[26:29], off sc0 sc1
	v_mul_f32_e32 v21, v21, v45
	s_nop 0
	v_mul_f32_e32 v26, v19, v41
	v_cvt_pk_bf16_f32 v19, v23, v24
	v_ashrrev_i32_e32 v23, 31, v22
	v_lshlrev_b64 v[22:23], 12, v[22:23]
	v_lshl_add_u64 v[10:11], v[10:11], 0, v[22:23]
	v_mul_f32_e32 v27, v20, v43
	v_cvt_pk_bf16_f32 v20, v25, v26
	v_cvt_pk_bf16_f32 v21, v27, v21
	global_store_dwordx4 v[10:11], v[18:21], off sc0 sc1
	s_waitcnt lgkmcnt(0)
	s_cbranch_scc1 .LBB0_707
	s_mov_b32 s24, s70

; #define LAS __attribute__((address_space(3)))
; __device__ __forceinline__ void conv_item(const float* __restrict__ W, int N, bf16_t* __restrict__ WT, int ldk, int mode, int row_off, int n_lo, int nblk, ...
;     const int kb = item / nblk, nb = item % nblk, k0 = 64 * kb, n0 = n_lo + 32 * nb;
;     const float s = sc * (sn ? sn[n0 + (lane & 31)] : 1.f);
;     const float* wp = W + (size_t)(k0 + (lane >> 5)) * N + n0 + (lane & 31);
;     float v[32];
; #pragma unroll
;     for (int i = 0; i < 32; ++i) v[i] = __builtin_nontemporal_load(wp + (size_t)(2 * i) * N);
.LBB0_711:
	s_mul_hi_i32 s2, s12, 0x2e8ba2e9
	s_lshr_b32 s3, s2, 31
	s_ashr_i32 s15, s2, 5
	s_add_i32 s15, s15, s3
	s_lshl_b32 s2, s15, 6
	s_mul_i32 s3, s15, 0xffffea00
	s_add_i32 s10, s0, s3
	v_or_b32_e32 v13, s2, v1
	v_mov_b64_e32 v[10:11], s[8:9]
	s_movk_i32 s3, 0x5800
	v_mad_i64_i32 v[10:11], s[24:25], v13, s3, v[10:11]
	s_ashr_i32 s11, s10, 31
	v_lshl_add_u64 v[10:11], s[10:11], 2, v[10:11]
	v_lshl_add_u64 v[36:37], v[10:11], 0, v[176:177]
	s_mov_b32 s3, 0xb000
	v_add_co_u32_e32 v10, vcc, s3, v36
	global_load_dword v35, v[36:37], off nt
	s_nop 0
	v_addc_co_u32_e32 v11, vcc, 0, v37, vcc
	global_load_dword v40, v[10:11], off nt
	v_add_co_u32_e32 v10, vcc, s26, v36
	s_mov_b32 s3, 0x21000
	s_nop 0
	v_addc_co_u32_e32 v11, vcc, 0, v37, vcc
	global_load_dword v41, v[10:11], off nt
	v_add_co_u32_e32 v10, vcc, s3, v36
	s_mov_b32 s3, 0x37000
	s_nop 0
	v_addc_co_u32_e32 v11, vcc, 0, v37, vcc
	global_load_dword v42, v[10:11], off nt
	v_add_co_u32_e32 v10, vcc, s27, v36
	s_mulk_i32 s15, 0xd400
	s_nop 0
	v_addc_co_u32_e32 v11, vcc, 0, v37, vcc
	global_load_dword v23, v[10:11], off nt
	v_add_co_u32_e32 v10, vcc, s3, v36
	s_mov_b32 s3, 0x42000
	s_nop 0
	v_addc_co_u32_e32 v11, vcc, 0, v37, vcc
	global_load_dword v24, v[10:11], off nt
	v_add_co_u32_e32 v10, vcc, s3, v36
	s_mov_b32 s3, 0x4d000
	s_nop 0
	v_addc_co_u32_e32 v11, vcc, 0, v37, vcc
	global_load_dword v25, v[10:11], off nt
	v_add_co_u32_e32 v10, vcc, s3, v36
	s_mov_b32 s3, 0x63000
	s_nop 0
	v_addc_co_u32_e32 v11, vcc, 0, v37, vcc
	global_load_dword v27, v[10:11], off nt
	v_add_co_u32_e32 v10, vcc, s28, v36
	s_add_i32 s11, s13, s15
	s_nop 0
	v_addc_co_u32_e32 v11, vcc, 0, v37, vcc
	global_load_dword v26, v[10:11], off nt
	v_add_co_u32_e32 v10, vcc, s3, v36
	s_mov_b32 s3, 0x6e000
	s_nop 0
	v_addc_co_u32_e32 v11, vcc, 0, v37, vcc
	global_load_dword v28, v[10:11], off nt
	v_add_co_u32_e32 v10, vcc, s3, v36
	s_mov_b32 s3, 0x79000
	s_nop 0
	v_addc_co_u32_e32 v11, vcc, 0, v37, vcc
	global_load_dword v29, v[10:11], off nt
	v_add_co_u32_e32 v10, vcc, s3, v36
	s_mov_b32 s3, 0x84000
	s_nop 0
	v_addc_co_u32_e32 v11, vcc, 0, v37, vcc
	global_load_dword v31, v[10:11], off nt
	v_add_co_u32_e32 v10, vcc, s3, v36
	s_mov_b32 s3, 0x8f000
	s_nop 0
	v_addc_co_u32_e32 v11, vcc, 0, v37, vcc
	global_load_dword v30, v[10:11], off nt
	v_add_co_u32_e32 v10, vcc, s3, v36
	s_mov_b32 s3, 0x9a000
	s_nop 0
	v_addc_co_u32_e32 v11, vcc, 0, v37, vcc
	global_load_dword v32, v[10:11], off nt
	v_add_co_u32_e32 v10, vcc, s3, v36
	s_mov_b32 s3, 0xa5000
	s_nop 0
	v_addc_co_u32_e32 v11, vcc, 0, v37, vcc
	global_load_dword v33, v[10:11], off nt
	v_add_co_u32_e32 v10, vcc, s3, v36
	s_mov_b32 s3, 0xbb000
	s_nop 0
	v_addc_co_u32_e32 v11, vcc, 0, v37, vcc
	global_load_dword v43, v[10:11], off nt
	v_add_co_u32_e32 v10, vcc, s68, v36
	s_and_b32 s11, s11, 0xffffff00
	s_nop 0
	v_addc_co_u32_e32 v11, vcc, 0, v37, vcc
	global_load_dword v34, v[10:11], off nt
	v_add_co_u32_e32 v10, vcc, s3, v36
	s_mov_b32 s3, 0xc6000
	s_nop 0
	v_addc_co_u32_e32 v11, vcc, 0, v37, vcc
	global_load_dword v44, v[10:11], off nt
	v_add_co_u32_e32 v10, vcc, s3, v36
	s_mov_b32 s3, 0xd1000
	s_nop 0
	v_addc_co_u32_e32 v11, vcc, 0, v37, vcc
	global_load_dword v45, v[10:11], off nt
	v_add_co_u32_e32 v10, vcc, s3, v36
	s_mov_b32 s3, 0xdc000
	s_nop 0
	v_addc_co_u32_e32 v11, vcc, 0, v37, vcc
	global_load_dword v46, v[10:11], off nt
	v_add_co_u32_e32 v10, vcc, s3, v36
	s_mov_b32 s3, 0xe7000
	s_nop 0
	v_addc_co_u32_e32 v11, vcc, 0, v37, vcc
	v_add_co_u32_e32 v14, vcc, s3, v36
	s_mov_b32 s3, 0xf2000
	s_nop 0
	v_addc_co_u32_e32 v15, vcc, 0, v37, vcc
	global_load_dword v10, v[10:11], off nt
	s_and_b32 s10, s10, 0x60
	global_load_dword v11, v[14:15], off nt
	v_add_co_u32_e32 v14, vcc, s3, v36
	s_mov_b32 s3, 0xfd000
	s_nop 0
	v_addc_co_u32_e32 v15, vcc, 0, v37, vcc
	global_load_dword v13, v[14:15], off nt
	v_add_co_u32_e32 v14, vcc, s3, v36
	s_mov_b32 s3, 0x108000
	s_nop 0
	v_addc_co_u32_e32 v15, vcc, 0, v37, vcc
	v_add_co_u32_e32 v16, vcc, s3, v36
	s_mov_b32 s3, 0x113000
	s_nop 0
	v_addc_co_u32_e32 v17, vcc, 0, v37, vcc
	global_load_dword v15, v[14:15], off nt
	s_or_b32 s10, s11, s10
	global_load_dword v14, v[16:17], off nt
	v_add_co_u32_e32 v16, vcc, s3, v36
	s_mov_b32 s3, 0x11e000
	s_nop 0
	v_addc_co_u32_e32 v17, vcc, 0, v37, vcc
	v_add_co_u32_e32 v18, vcc, s3, v36
	s_mov_b32 s3, 0x129000
	s_nop 0
	v_addc_co_u32_e32 v19, vcc, 0, v37, vcc
	global_load_dword v16, v[16:17], off nt
	s_add_i32 s12, s12, s88
	global_load_dword v17, v[18:19], off nt
	v_add_co_u32_e32 v18, vcc, s3, v36
	s_mov_b32 s3, 0x134000
	s_nop 0
	v_addc_co_u32_e32 v19, vcc, 0, v37, vcc
	v_add_co_u32_e32 v20, vcc, s3, v36
	s_mov_b32 s3, 0x13f000
	s_nop 0
	v_addc_co_u32_e32 v21, vcc, 0, v37, vcc
	global_load_dword v19, v[18:19], off nt
	s_add_i32 s0, s0, s1
	global_load_dword v18, v[20:21], off nt
	v_add_co_u32_e32 v20, vcc, s3, v36
	s_mov_b32 s3, 0x14a000
	s_nop 0
	v_addc_co_u32_e32 v21, vcc, 0, v37, vcc
	v_add_co_u32_e32 v38, vcc, s3, v36
	s_mov_b32 s3, 0x155000
	s_nop 0
	v_addc_co_u32_e32 v39, vcc, 0, v37, vcc
	v_add_co_u32_e32 v36, vcc, s3, v36
	global_load_dword v20, v[20:21], off nt
	s_nop 0
	v_addc_co_u32_e32 v37, vcc, 0, v37, vcc
	global_load_dword v22, v[36:37], off nt
	global_load_dword v21, v[38:39], off nt
	s_waitcnt vmcnt(0)
; #define LAS __attribute__((address_space(3)))
; __device__ __forceinline__ unsigned cvt_pk_bf16(float lo, float hi) { unsigned r; asm("v_cvt_pk_bf16_f32 %0, %1, %2" : "=v"(r) : "v"(lo), "v"(hi)); return r; }
; __device__ __forceinline__ unsigned cvt_pk_f16(float lo, float hi) { if (X_BF16) return cvt_pk_bf16(lo, hi); const h16x2 v = {(_Float16)lo, (_Float16)hi}; return __builtin_bit_cast(unsigned, v); }
; __device__ __forceinline__ void conv_item(const float* __restrict__ W, int N, bf16_t* __restrict__ WT, int ldk, int mode, int row_off, int n_lo, int nblk, ...
;     ...
;     for (int i = 0; i < 32; ++i) scr[(2 * i + (lane >> 5)) * 33 + (lane & 31)] = v[i] * s;
;     asm volatile("s_waitcnt lgkmcnt(0)" ::: "memory");
;     const int c = lane & 7;
;     f32x4 g0 = {1.f, 1.f, 1.f, 1.f}, g1 = g0;
;     if (gk) { g0 = *(const f32x4*)(gk + k0 + 8 * c); g1 = *(const f32x4*)(gk + k0 + 8 * c + 4); }
;     const int nn0 = n0 - n_lo;
;     const int drow0 = (mode == 0) ? row_off + nn0 : 256 * (nn0 >> 7) + 128 * (mode - 1) + (nn0 & 127);
; #pragma unroll
;     for (int j = 0; j < 4; ++j) { const int n = (lane >> 3) + 8 * j; const LAS float* sp = scr + (8 * c) * 33 + n;
;         const float e0 = sp[0 * 33] * g0[0], e1 = sp[1 * 33] * g0[1], e2 = sp[2 * 33] * g0[2], e3 = sp[3 * 33] * g0[3], e4 = sp[4 * 33] * g1[0], e5 = sp[5 * 33] * g1[1], e6 = sp[6 * 33] * g1[2], e7 = sp[7 * 33] * g1[3];
;         u32x4 o;
;         if (f16) { o.x = pg8::cvt_pk_f16(e0, e1); o.y = pg8::cvt_pk_f16(e2, e3); o.z = pg8::cvt_pk_f16(e4, e5); o.w = pg8::cvt_pk_f16(e6, e7); }
;         else { o.x = cvt_pk_bf16(e0, e1); o.y = cvt_pk_bf16(e2, e3); o.z = cvt_pk_bf16(e4, e5); o.w = cvt_pk_bf16(e6, e7); }
;         *(u32x4*)(WT + (size_t)(drow0 + n) * ldk + k0 + 8 * c) = o; }
;     asm volatile("s_waitcnt lgkmcnt(0)" ::: "memory");
	ds_write2_b32 v0, v35, v40 offset1:66
	ds_write2_b32 v0, v41, v42 offset0:132 offset1:198
	v_add_u32_e32 v35, 0x400, v0
	ds_write2_b32 v35, v23, v24 offset0:8 offset1:74
	ds_write2_b32 v35, v25, v27 offset0:140 offset1:206
	v_add_u32_e32 v23, 0x800, v0
	ds_write2_b32 v23, v26, v28 offset0:16 offset1:82
	ds_write2_b32 v23, v29, v31 offset0:148 offset1:214
	v_add_u32_e32 v23, 0xc00, v0
	ds_write2_b32 v23, v30, v32 offset0:24 offset1:90
	ds_write2_b32 v23, v33, v43 offset0:156 offset1:222
	v_add_u32_e32 v23, 0x1000, v0
	ds_write2_b32 v23, v34, v44 offset0:32 offset1:98
	ds_write2_b32 v23, v45, v46 offset0:164 offset1:230
	v_add_u32_e32 v23, 0x1400, v0
	ds_write2_b32 v23, v10, v11 offset0:40 offset1:106
	ds_write2_b32 v23, v13, v15 offset0:172 offset1:238
	v_add_u32_e32 v10, 0x1800, v0
	ds_write2_b32 v10, v14, v16 offset0:48 offset1:114
	ds_write2_b32 v10, v17, v19 offset0:180 offset1:246
	v_add_u32_e32 v10, 0x1c00, v0
	ds_write2_b32 v10, v18, v20 offset0:56 offset1:122
	ds_write2_b32 v10, v21, v22 offset0:188 offset1:254
	s_ashr_i32 s3, s2, 31
	s_waitcnt lgkmcnt(0)
	v_lshl_add_u64 v[10:11], s[2:3], 2, v[4:5]
	global_load_dwordx4 v[14:17], v[10:11], off offset:16
	global_load_dwordx4 v[18:21], v[10:11], off
	ds_read2_b32 v[30:31], v6 offset0:66 offset1:74
	ds_read2_b32 v[32:33], v6 offset0:99 offset1:107
	ds_read2_b32 v[26:27], v6 offset1:8
	ds_read2_b32 v[28:29], v6 offset0:33 offset1:41
	ds_read2_b32 v[34:35], v6 offset0:132 offset1:140
	ds_read2_b32 v[36:37], v6 offset0:165 offset1:173
	ds_read2_b32 v[38:39], v6 offset0:198 offset1:206
	ds_read2_b32 v[40:41], v6 offset0:231 offset1:239
	v_or_b32_e32 v42, s10, v12
	v_ashrrev_i32_e32 v43, 31, v42
	v_lshl_add_u64 v[10:11], s[2:3], 1, v[2:3]
	v_lshlrev_b64 v[42:43], 12, v[42:43]
	v_lshl_add_u64 v[42:43], v[10:11], 0, v[42:43]
	s_add_i32 s13, s13, s14
	s_cmpk_lt_i32 s12, 0x1600
	s_waitcnt vmcnt(1) lgkmcnt(3)
	v_mul_f32_e32 v25, v14, v34
	s_waitcnt vmcnt(0)
	v_mul_f32_e32 v23, v20, v30
	v_mul_f32_e32 v24, v21, v32
	v_mul_f32_e32 v13, v18, v26
	v_mul_f32_e32 v22, v19, v28
	s_waitcnt lgkmcnt(2)
	v_mul_f32_e32 v26, v15, v36
	v_cvt_pk_bf16_f32 v23, v23, v24
	v_cvt_pk_bf16_f32 v24, v25, v26
	s_waitcnt lgkmcnt(1)
	v_mul_f32_e32 v28, v16, v38
	s_waitcnt lgkmcnt(0)
	v_mul_f32_e32 v30, v17, v40
	v_cvt_pk_bf16_f32 v22, v13, v22
	v_cvt_pk_bf16_f32 v25, v28, v30
	global_store_dwordx4 v[42:43], v[22:25], off sc0 sc1
	v_mul_f32_e32 v26, v15, v37
	v_mul_f32_e32 v13, v18, v27
	v_mul_f32_e32 v23, v20, v31
	v_mul_f32_e32 v24, v21, v33
	v_mul_f32_e32 v25, v14, v35
	v_mul_f32_e32 v27, v16, v39
	v_cvt_pk_bf16_f32 v23, v23, v24
	v_cvt_pk_bf16_f32 v24, v25, v26
	v_or_b32_e32 v26, s10, v7
	v_mul_f32_e32 v28, v17, v41
	v_cvt_pk_bf16_f32 v25, v27, v28
	v_ashrrev_i32_e32 v27, 31, v26
	v_lshlrev_b64 v[26:27], 12, v[26:27]
	v_mul_f32_e32 v22, v19, v29
	v_lshl_add_u64 v[26:27], v[10:11], 0, v[26:27]
	v_cvt_pk_bf16_f32 v22, v13, v22
	global_store_dwordx4 v[26:27], v[22:25], off sc0 sc1
	ds_read2_b32 v[26:27], v6 offset0:16 offset1:24
	ds_read2_b32 v[28:29], v6 offset0:49 offset1:57
	ds_read2_b32 v[30:31], v6 offset0:82 offset1:90
	ds_read2_b32 v[32:33], v6 offset0:115 offset1:123
	ds_read2_b32 v[34:35], v6 offset0:148 offset1:156
	ds_read2_b32 v[36:37], v6 offset0:181 offset1:189
	ds_read2_b32 v[38:39], v6 offset0:214 offset1:222
	ds_read2_b32 v[40:41], v6 offset0:247 offset1:255
	v_or_b32_e32 v42, s10, v8
	s_waitcnt lgkmcnt(7)
	v_mul_f32_e32 v13, v18, v26
	s_waitcnt lgkmcnt(6)
	v_mul_f32_e32 v22, v19, v28
	v_ashrrev_i32_e32 v43, 31, v42
	v_cvt_pk_bf16_f32 v22, v13, v22
	v_lshlrev_b64 v[42:43], 12, v[42:43]
	v_mul_f32_e32 v13, v18, v27
	v_mul_f32_e32 v18, v19, v29
	s_waitcnt lgkmcnt(5)
	v_mul_f32_e32 v23, v20, v30
	s_waitcnt lgkmcnt(4)
	v_mul_f32_e32 v24, v21, v32
	s_waitcnt lgkmcnt(3)
	v_mul_f32_e32 v25, v14, v34
	v_lshl_add_u64 v[42:43], v[10:11], 0, v[42:43]
	v_mul_f32_e32 v19, v20, v31
	v_mul_f32_e32 v20, v21, v33
	v_mul_f32_e32 v21, v14, v35
	v_cvt_pk_bf16_f32 v14, v13, v18
	v_or_b32_e32 v18, s10, v9
	s_waitcnt lgkmcnt(2)
	v_mul_f32_e32 v26, v15, v36
	s_waitcnt lgkmcnt(1)
	v_mul_f32_e32 v28, v16, v38
	s_waitcnt lgkmcnt(0)
	v_mul_f32_e32 v30, v17, v40
	v_cvt_pk_bf16_f32 v23, v23, v24
	v_cvt_pk_bf16_f32 v24, v25, v26
	v_cvt_pk_bf16_f32 v25, v28, v30
	global_store_dwordx4 v[42:43], v[22:25], off sc0 sc1
	v_mul_f32_e32 v17, v17, v41
	s_nop 0
	v_mul_f32_e32 v22, v15, v37
	v_cvt_pk_bf16_f32 v15, v19, v20
	v_ashrrev_i32_e32 v19, 31, v18
	v_lshlrev_b64 v[18:19], 12, v[18:19]
	v_lshl_add_u64 v[10:11], v[10:11], 0, v[18:19]
	v_mul_f32_e32 v23, v16, v39
	v_cvt_pk_bf16_f32 v16, v21, v22
	v_cvt_pk_bf16_f32 v17, v23, v17
	global_store_dwordx4 v[10:11], v[14:17], off sc0 sc1
	s_waitcnt lgkmcnt(0)
	s_cbranch_scc1 .LBB0_711
	s_mov_b32 s24, s30
